# grid barrier first-use setup: the 16 per-XCD counter loads of the one-time completion poll issued back to back with one wait instead of 16 serial round trips
# speedup vs baseline: 1.0024x; 1.0024x over previous
; __device__ __forceinline__ unsigned xb_ld(unsigned* p)              { return __hip_atomic_load(p, __ATOMIC_RELAXED, __HIP_MEMORY_SCOPE_AGENT); }
; __device__ __forceinline__ void xcd_barrier_complete(unsigned* bar, unsigned x, unsigned& nloc, unsigned& nx) {
;     const unsigned G = gridDim.x * gridDim.y * gridDim.z;
;     unsigned sum, cnt, mine, sp = 0u;
;     for (;;) {
;         sum = 0u; cnt = 0u; mine = 0u;
; #pragma unroll
;         for (unsigned j = 0; j < 16; ++j) { const unsigned c = xb_ld(&bar[XB_XCNT(j)]); sum += c; cnt += (c > 0u) ? 1u : 0u; mine = (j == x) ? c : mine; }
;         if (sum == G) break;
;         __builtin_amdgcn_s_sleep(1);
;         if ((++sp & 255u) == 0u) { if (xb_ld(&bar[XB_TMO])) break; if (sp > XB_SPIN_CAP) { atomicAdd(&bar[XB_TMO], 1u); break; } }
;     }
;     nloc = mine > 0u ? mine : 1u; nx = cnt > 0u ? cnt : 1u;
; }
.LBB0_335:
	s_mov_b64 s[4:5], -1
	v_readlane_b32 s2, v252, 4
	v_readlane_b32 s3, v252, 5
	s_nop 4
	global_load_dword v0, v1, s[2:3] sc1
	v_readlane_b32 s2, v252, 6
	v_readlane_b32 s3, v252, 7
	s_nop 4
	global_load_dword v2, v1, s[2:3] sc1
	v_readlane_b32 s2, v252, 8
	v_readlane_b32 s3, v252, 9
	s_nop 4
	global_load_dword v3, v1, s[2:3] sc1
	v_readlane_b32 s2, v252, 10
	v_readlane_b32 s3, v252, 11
	s_nop 4
	global_load_dword v4, v1, s[2:3] sc1
	v_readlane_b32 s2, v252, 12
	v_readlane_b32 s3, v252, 13
	s_nop 4
	global_load_dword v5, v1, s[2:3] sc1
	v_readlane_b32 s2, v252, 14
	v_readlane_b32 s3, v252, 15
	s_nop 4
	global_load_dword v6, v1, s[2:3] sc1
	v_readlane_b32 s2, v252, 16
	v_readlane_b32 s3, v252, 17
	s_nop 4
	global_load_dword v7, v1, s[2:3] sc1
	v_readlane_b32 s2, v252, 18
	v_readlane_b32 s3, v252, 19
	s_nop 4
	global_load_dword v8, v1, s[2:3] sc1
	v_readlane_b32 s2, v252, 20
	v_readlane_b32 s3, v252, 21
	s_nop 4
	global_load_dword v9, v1, s[2:3] sc1
	v_readlane_b32 s2, v252, 22
	v_readlane_b32 s3, v252, 23
	s_nop 4
	global_load_dword v10, v1, s[2:3] sc1
	v_readlane_b32 s2, v252, 24
	v_readlane_b32 s3, v252, 25
	s_nop 4
	global_load_dword v11, v1, s[2:3] sc1
	v_readlane_b32 s2, v252, 26
	v_readlane_b32 s3, v252, 27
	s_nop 4
	global_load_dword v12, v1, s[2:3] sc1
	v_readlane_b32 s2, v252, 28
	v_readlane_b32 s3, v252, 29
	s_nop 4
	global_load_dword v13, v1, s[2:3] sc1
	v_readlane_b32 s2, v252, 30
	v_readlane_b32 s3, v252, 31
	s_nop 4
	global_load_dword v14, v1, s[2:3] sc1
	v_readlane_b32 s2, v252, 32
	v_readlane_b32 s3, v252, 33
	s_nop 4
	global_load_dword v15, v1, s[2:3] sc1
	v_readlane_b32 s2, v252, 34
	v_readlane_b32 s3, v252, 35
	s_nop 4
	global_load_dword v16, v1, s[2:3] sc1
	s_mov_b64 s[2:3], -1
	s_waitcnt vmcnt(0)
	v_add_u32_e32 v17, v2, v0
	v_add_u32_e32 v17, v17, v3
	v_add_u32_e32 v17, v17, v4
	v_add_u32_e32 v17, v17, v5
	v_add_u32_e32 v17, v17, v6
	v_add_u32_e32 v17, v17, v7
	v_add_u32_e32 v17, v17, v8
	v_add_u32_e32 v17, v17, v9
	v_add_u32_e32 v17, v17, v10
	v_add_u32_e32 v17, v17, v11
	v_add_u32_e32 v17, v17, v12
	v_add_u32_e32 v17, v17, v13
	v_add_u32_e32 v17, v17, v14
	v_add_u32_e32 v17, v17, v15
	v_add_u32_e32 v17, v17, v16
	v_cmp_eq_u32_e32 vcc, s8, v17
	s_cbranch_vccnz .LBB0_334
	s_and_b32 s2, s9, 0xff
	s_cmp_eq_u32 s2, 0
	s_mov_b64 s[2:3], -1
	s_mov_b64 s[6:7], -1
	s_sleep 1
	s_cbranch_scc0 .LBB0_339
	v_readlane_b32 s2, v252, 2
	v_readlane_b32 s3, v252, 3
	s_nop 4
	global_load_dword v17, v1, s[2:3] sc1
	s_waitcnt vmcnt(0)
	v_cmp_eq_u32_e32 vcc, 0, v17
	s_cbranch_vccnz .LBB0_341
	s_mov_b64 s[6:7], 0
	s_mov_b64 s[2:3], -1
